# v046 + sample-row tail hand-written with the final RMSNorm fused; last grid barrier and the separate final phase removed
# speedup vs baseline: 1.0121x; 1.0025x over previous
; __device__ __forceinline__ void ffd_sample_rows(const Args& a, int vcu, int G, float* ssout) {
;     const int tid = threadIdx.x, lane = tid & 63, wave = tid >> 6;
;     const int gw = vcu * 8 + wave, NGW = G * 8;
;     float* XR = (float*)(a.ws + WS_XR); bf16_t* XB = (bf16_t*)(a.ws + WS_XB); const float* PART = (const float*)(a.ws + WS_PART);
;     for (int r = gw; r < MS; r += NGW) {
;         const int pml = r >> 8, rr = r & 255; const size_t row = (size_t)(MP + r);
;         f32x4 acc[4];
; #pragma unroll
;         for (int pn = 0; pn < 4; ++pn) { acc[pn] = *(const f32x4*)(XR + row * DM + pn * 256 + 4 * lane);
; #pragma unroll
;             for (int sl = 0; sl < 8; ++sl) acc[pn] += *(const f32x4*)(PART + ((size_t)((pml * 4 + pn) * 8 + sl) * 256 + rr) * 256 + 4 * lane); }
.LBB0_2202:
	s_or_b64 exec, exec, s[4:5]
	s_lshr_b32 s3, s3, 29
	s_add_i32 s3, s2, s3
	s_ashr_i32 s4, s3, 3
	s_lshl_b32 s5, s2, 8
	s_mul_i32 s2, s4, 0xfffff808
	s_waitcnt lgkmcnt(0)
	v_or_b32_e32 v2, s5, v1
	v_add_u32_e32 v82, s2, v2
	s_movk_i32 s2, 0x800
	v_cmp_gt_i32_e32 vcc, s2, v82
	s_barrier
	v_lshl_or_b32 v2, s96, 3, v1
	v_and_b32_e32 v3, 63, v0
	v_lshlrev_b32_e32 v3, 4, v3
	v_add_u32_e32 v4, 0x4000, v2
	v_lshlrev_b32_e32 v4, 12, v4
	v_add_u32_e32 v4, v4, v3
	v_lshrrev_b32_e32 v5, 8, v2
	v_lshlrev_b32_e32 v5, 23, v5
	v_and_b32_e32 v6, 0xff, v2
	v_lshl_add_u32 v5, v6, 10, v5
	v_add_u32_e32 v5, v5, v3
	s_add_u32 s4, s28, 0x5a00000
	s_addc_u32 s5, s29, 0
	s_add_u32 s6, s28, 0x25e00000
	s_addc_u32 s7, s29, 0
	v_readlane_b32 s8, v252, 6
	v_readlane_b32 s9, v252, 7
	v_readlane_b32 s10, v252, 4
	v_readlane_b32 s11, v252, 5
	s_nop 4
	global_load_dwordx4 v[10:13], v4, s[4:5]
	global_load_dwordx4 v[14:17], v4, s[4:5] offset:1024
	global_load_dwordx4 v[18:21], v4, s[4:5] offset:2048
	global_load_dwordx4 v[22:25], v4, s[4:5] offset:3072
	global_load_dwordx4 v[160:163], v3, s[10:11]
	global_load_dwordx4 v[164:167], v3, s[10:11] offset:1024
	global_load_dwordx4 v[168:171], v3, s[10:11] offset:2048
	global_load_dwordx4 v[172:175], v3, s[10:11] offset:3072
	global_load_dwordx4 v[30:33], v5, s[6:7]
	v_add_u32_e32 v7, 0x40000, v5
	global_load_dwordx4 v[34:37], v7, s[6:7]
	v_add_u32_e32 v7, 0x80000, v5
	global_load_dwordx4 v[38:41], v7, s[6:7]
	v_add_u32_e32 v7, 0xc0000, v5
	global_load_dwordx4 v[42:45], v7, s[6:7]
	v_add_u32_e32 v7, 0x100000, v5
	global_load_dwordx4 v[46:49], v7, s[6:7]
	v_add_u32_e32 v7, 0x140000, v5
	global_load_dwordx4 v[50:53], v7, s[6:7]
	v_add_u32_e32 v7, 0x180000, v5
	global_load_dwordx4 v[54:57], v7, s[6:7]
	v_add_u32_e32 v7, 0x1c0000, v5
	global_load_dwordx4 v[58:61], v7, s[6:7]
	v_add_u32_e32 v7, 0x200000, v5
	global_load_dwordx4 v[62:65], v7, s[6:7]
	v_add_u32_e32 v7, 0x240000, v5
	global_load_dwordx4 v[66:69], v7, s[6:7]
	v_add_u32_e32 v7, 0x280000, v5
	global_load_dwordx4 v[70:73], v7, s[6:7]
	v_add_u32_e32 v7, 0x2c0000, v5
	global_load_dwordx4 v[74:77], v7, s[6:7]
	v_add_u32_e32 v7, 0x300000, v5
	global_load_dwordx4 v[78:81], v7, s[6:7]
	v_add_u32_e32 v7, 0x340000, v5
	global_load_dwordx4 v[82:85], v7, s[6:7]
	v_add_u32_e32 v7, 0x380000, v5
	global_load_dwordx4 v[86:89], v7, s[6:7]
	v_add_u32_e32 v7, 0x3c0000, v5
	global_load_dwordx4 v[90:93], v7, s[6:7]
	v_add_u32_e32 v7, 0x400000, v5
	global_load_dwordx4 v[94:97], v7, s[6:7]
	v_add_u32_e32 v7, 0x440000, v5
	global_load_dwordx4 v[98:101], v7, s[6:7]
	v_add_u32_e32 v7, 0x480000, v5
	global_load_dwordx4 v[102:105], v7, s[6:7]
	v_add_u32_e32 v7, 0x4c0000, v5
	global_load_dwordx4 v[106:109], v7, s[6:7]
	v_add_u32_e32 v7, 0x500000, v5
	global_load_dwordx4 v[110:113], v7, s[6:7]
	v_add_u32_e32 v7, 0x540000, v5
	global_load_dwordx4 v[114:117], v7, s[6:7]
	v_add_u32_e32 v7, 0x580000, v5
	global_load_dwordx4 v[118:121], v7, s[6:7]
	v_add_u32_e32 v7, 0x5c0000, v5
	global_load_dwordx4 v[122:125], v7, s[6:7]
	v_add_u32_e32 v7, 0x600000, v5
	global_load_dwordx4 v[126:129], v7, s[6:7]
	v_add_u32_e32 v7, 0x640000, v5
	global_load_dwordx4 v[130:133], v7, s[6:7]
	v_add_u32_e32 v7, 0x680000, v5
	global_load_dwordx4 v[134:137], v7, s[6:7]
	v_add_u32_e32 v7, 0x6c0000, v5
	global_load_dwordx4 v[138:141], v7, s[6:7]
	v_add_u32_e32 v7, 0x700000, v5
	global_load_dwordx4 v[142:145], v7, s[6:7]
	v_add_u32_e32 v7, 0x740000, v5
	global_load_dwordx4 v[146:149], v7, s[6:7]
	v_add_u32_e32 v7, 0x780000, v5
	global_load_dwordx4 v[150:153], v7, s[6:7]
	v_add_u32_e32 v7, 0x7c0000, v5
	global_load_dwordx4 v[154:157], v7, s[6:7]
	s_waitcnt vmcnt(0)
; __device__ __forceinline__ unsigned pk(float lo, float hi) { return pg8::cvt_pk_bf16(lo, hi); }
; __device__ __forceinline__ float dot4(f32x4 v) { return (v[0] * v[0] + v[1] * v[1]) + (v[2] * v[2] + v[3] * v[3]); }
; __device__ __forceinline__ void p_final(const Args& a, int vcu, int G) {
;     ...
;         for (int q = 0; q < 3; ++q) { const int m = m0 + q * NGW; if (m < MT) { rs[q] = rsqrtf(ss[m] * (1.f / DM) + EPS);
; #pragma unroll
;             for (int j = 0; j < 4; ++j) v[q][j] = __builtin_nontemporal_load((const f32x4*)(XR + (size_t)m * DM) + lane + 64 * j); } }
; #pragma unroll
;         for (int q = 0; q < 3; ++q) { const int m = m0 + q * NGW; if (m < MT) {
; #pragma unroll
;             for (int j = 0; j < 4; ++j) __builtin_nontemporal_store(v[q][j] * rs[q] * gv[j], (f32x4*)(a.out + O_Y + (size_t)m * DM) + lane + 64 * j); } }
; __device__ __forceinline__ void ffd_sample_rows(const Args& a, int vcu, int G, float* ssout) {
;     ...
;             for (int sl = 0; sl < 8; ++sl) acc[pn] += *(const f32x4*)(PART + ((size_t)((pml * 4 + pn) * 8 + sl) * 256 + rr) * 256 + 4 * lane); }
;         float sq = 0.f;
; #pragma unroll
;         for (int pn = 0; pn < 4; ++pn) { sq += dot4(acc[pn]); *(f32x4*)(XR + row * DM + pn * 256 + 4 * lane) = acc[pn];
;             u32x2 o; o.x = pk(acc[pn][0], acc[pn][1]); o.y = pk(acc[pn][2], acc[pn][3]); *(u32x2*)(XB + row * DM + pn * 256 + 4 * lane) = o; }
;         sq = wave_sum(sq);
;         if (lane == 0) ssout[row] = sq;
;     }
	v_pk_add_f32 v[10:11], v[10:11], v[30:31]
	v_pk_add_f32 v[12:13], v[12:13], v[32:33]
	v_pk_add_f32 v[10:11], v[10:11], v[34:35]
	v_pk_add_f32 v[12:13], v[12:13], v[36:37]
	v_pk_add_f32 v[10:11], v[10:11], v[38:39]
	v_pk_add_f32 v[12:13], v[12:13], v[40:41]
	v_pk_add_f32 v[10:11], v[10:11], v[42:43]
	v_pk_add_f32 v[12:13], v[12:13], v[44:45]
	v_pk_add_f32 v[10:11], v[10:11], v[46:47]
	v_pk_add_f32 v[12:13], v[12:13], v[48:49]
	v_pk_add_f32 v[10:11], v[10:11], v[50:51]
	v_pk_add_f32 v[12:13], v[12:13], v[52:53]
	v_pk_add_f32 v[10:11], v[10:11], v[54:55]
	v_pk_add_f32 v[12:13], v[12:13], v[56:57]
	v_pk_add_f32 v[10:11], v[10:11], v[58:59]
	v_pk_add_f32 v[12:13], v[12:13], v[60:61]
	v_pk_add_f32 v[14:15], v[14:15], v[62:63]
	v_pk_add_f32 v[16:17], v[16:17], v[64:65]
	v_pk_add_f32 v[14:15], v[14:15], v[66:67]
	v_pk_add_f32 v[16:17], v[16:17], v[68:69]
	v_pk_add_f32 v[14:15], v[14:15], v[70:71]
	v_pk_add_f32 v[16:17], v[16:17], v[72:73]
	v_pk_add_f32 v[14:15], v[14:15], v[74:75]
	v_pk_add_f32 v[16:17], v[16:17], v[76:77]
	v_pk_add_f32 v[14:15], v[14:15], v[78:79]
	v_pk_add_f32 v[16:17], v[16:17], v[80:81]
	v_pk_add_f32 v[14:15], v[14:15], v[82:83]
	v_pk_add_f32 v[16:17], v[16:17], v[84:85]
	v_pk_add_f32 v[14:15], v[14:15], v[86:87]
	v_pk_add_f32 v[16:17], v[16:17], v[88:89]
	v_pk_add_f32 v[14:15], v[14:15], v[90:91]
	v_pk_add_f32 v[16:17], v[16:17], v[92:93]
	v_pk_add_f32 v[18:19], v[18:19], v[94:95]
	v_pk_add_f32 v[20:21], v[20:21], v[96:97]
	v_pk_add_f32 v[18:19], v[18:19], v[98:99]
	v_pk_add_f32 v[20:21], v[20:21], v[100:101]
	v_pk_add_f32 v[18:19], v[18:19], v[102:103]
	v_pk_add_f32 v[20:21], v[20:21], v[104:105]
	v_pk_add_f32 v[18:19], v[18:19], v[106:107]
	v_pk_add_f32 v[20:21], v[20:21], v[108:109]
	v_pk_add_f32 v[18:19], v[18:19], v[110:111]
	v_pk_add_f32 v[20:21], v[20:21], v[112:113]
	v_pk_add_f32 v[18:19], v[18:19], v[114:115]
	v_pk_add_f32 v[20:21], v[20:21], v[116:117]
	v_pk_add_f32 v[18:19], v[18:19], v[118:119]
	v_pk_add_f32 v[20:21], v[20:21], v[120:121]
	v_pk_add_f32 v[18:19], v[18:19], v[122:123]
	v_pk_add_f32 v[20:21], v[20:21], v[124:125]
	v_pk_add_f32 v[22:23], v[22:23], v[126:127]
	v_pk_add_f32 v[24:25], v[24:25], v[128:129]
	v_pk_add_f32 v[22:23], v[22:23], v[130:131]
	v_pk_add_f32 v[24:25], v[24:25], v[132:133]
	v_pk_add_f32 v[22:23], v[22:23], v[134:135]
	v_pk_add_f32 v[24:25], v[24:25], v[136:137]
	v_pk_add_f32 v[22:23], v[22:23], v[138:139]
	v_pk_add_f32 v[24:25], v[24:25], v[140:141]
	v_pk_add_f32 v[22:23], v[22:23], v[142:143]
	v_pk_add_f32 v[24:25], v[24:25], v[144:145]
	v_pk_add_f32 v[22:23], v[22:23], v[146:147]
	v_pk_add_f32 v[24:25], v[24:25], v[148:149]
	v_pk_add_f32 v[22:23], v[22:23], v[150:151]
	v_pk_add_f32 v[24:25], v[24:25], v[152:153]
	v_pk_add_f32 v[22:23], v[22:23], v[154:155]
	v_pk_add_f32 v[24:25], v[24:25], v[156:157]
	v_mul_f32_e32 v8, v10, v10
	v_fmac_f32_e32 v8, v11, v11
	v_fmac_f32_e32 v8, v12, v12
	v_fmac_f32_e32 v8, v13, v13
	v_fmac_f32_e32 v8, v14, v14
	v_fmac_f32_e32 v8, v15, v15
	v_fmac_f32_e32 v8, v16, v16
	v_fmac_f32_e32 v8, v17, v17
	v_fmac_f32_e32 v8, v18, v18
	v_fmac_f32_e32 v8, v19, v19
	v_fmac_f32_e32 v8, v20, v20
	v_fmac_f32_e32 v8, v21, v21
	v_fmac_f32_e32 v8, v22, v22
	v_fmac_f32_e32 v8, v23, v23
	v_fmac_f32_e32 v8, v24, v24
	v_fmac_f32_e32 v8, v25, v25
	s_nop 1
	v_add_f32_dpp v8, v8, v8 row_shr:1 row_mask:0xf bank_mask:0xf
	s_nop 1
	v_add_f32_dpp v8, v8, v8 row_shr:2 row_mask:0xf bank_mask:0xf
	s_nop 1
	v_add_f32_dpp v8, v8, v8 row_shr:4 row_mask:0xf bank_mask:0xf
	s_nop 1
	v_add_f32_dpp v8, v8, v8 row_shr:8 row_mask:0xf bank_mask:0xf
	s_nop 1
	v_add_f32_dpp v8, v8, v8 row_bcast:15 row_mask:0xa bank_mask:0xf
	s_nop 1
	v_add_f32_dpp v8, v8, v8 row_bcast:31 row_mask:0xc bank_mask:0xf
	s_nop 1
	v_readlane_b32 s12, v8, 63
	v_mov_b32_e32 v9, 0x358637bd
	s_nop 2
	v_mov_b32_e32 v8, s12
	v_fmamk_f32 v8, v8, 0x3a800000, v9
	v_mul_f32_e32 v9, 0x4b800000, v8
	v_cmp_gt_f32_e32 vcc, 0x800000, v8
	s_nop 1
	v_cndmask_b32_e32 v8, v8, v9, vcc
	v_rsq_f32_e32 v8, v8
	s_nop 0
	v_mul_f32_e32 v9, 0x45800000, v8
	v_cndmask_b32_e32 v8, v8, v9, vcc
	v_pk_mul_f32 v[10:11], v[10:11], v[8:9] op_sel_hi:[1,0]
	v_pk_mul_f32 v[12:13], v[12:13], v[8:9] op_sel_hi:[1,0]
	v_pk_mul_f32 v[10:11], v[10:11], v[160:161]
	v_pk_mul_f32 v[12:13], v[12:13], v[162:163]
	global_store_dwordx4 v4, v[10:13], s[8:9] nt
	v_pk_mul_f32 v[14:15], v[14:15], v[8:9] op_sel_hi:[1,0]
	v_pk_mul_f32 v[16:17], v[16:17], v[8:9] op_sel_hi:[1,0]
	v_pk_mul_f32 v[14:15], v[14:15], v[164:165]
	v_pk_mul_f32 v[16:17], v[16:17], v[166:167]
	global_store_dwordx4 v4, v[14:17], s[8:9] offset:1024 nt
	v_pk_mul_f32 v[18:19], v[18:19], v[8:9] op_sel_hi:[1,0]
	v_pk_mul_f32 v[20:21], v[20:21], v[8:9] op_sel_hi:[1,0]
	v_pk_mul_f32 v[18:19], v[18:19], v[168:169]
	v_pk_mul_f32 v[20:21], v[20:21], v[170:171]
	global_store_dwordx4 v4, v[18:21], s[8:9] offset:2048 nt
	v_pk_mul_f32 v[22:23], v[22:23], v[8:9] op_sel_hi:[1,0]
	v_pk_mul_f32 v[24:25], v[24:25], v[8:9] op_sel_hi:[1,0]
	v_pk_mul_f32 v[22:23], v[22:23], v[172:173]
	v_pk_mul_f32 v[24:25], v[24:25], v[174:175]
	global_store_dwordx4 v4, v[22:25], s[8:9] offset:3072 nt
	s_branch .LBB0_2270
	s_and_saveexec_b64 s[2:3], vcc
	s_cbranch_execz .LBB0_2207
	v_add_u32_e32 v2, s5, v1
	s_mulk_i32 s4, 0x7f8
	v_subrev_u32_e32 v2, s4, v2
	v_add_u32_e32 v2, 0x4000, v2
	v_ashrrev_i32_e32 v3, 31, v2
	v_mov_b64_e32 v[4:5], 0x90000
	v_lshl_add_u64 v[70:71], v[2:3], 2, v[4:5]
	v_lshlrev_b64 v[72:73], 12, v[2:3]
	v_lshlrev_b64 v[74:75], 11, v[2:3]
	v_mbcnt_lo_u32_b32 v2, -1, 0
	v_and_b32_e32 v6, 63, v0
	v_mbcnt_hi_u32_b32 v84, -1, v2
	v_lshlrev_b32_e32 v66, 4, v6
	v_mov_b32_e32 v67, 0
	v_and_b32_e32 v2, 64, v84
	v_lshl_add_u64 v[68:69], s[0:1], 0, v[66:67]
	v_cmp_eq_u32_e64 s[0:1], 0, v6
	v_lshlrev_b32_e32 v83, 8, v82
	v_or_b32_e32 v72, v72, v66
	v_lshl_or_b32 v74, v6, 3, v74
	s_mov_b64 s[4:5], 0
	s_mov_b32 s14, 0x3600000
	v_add_u32_e32 v85, 64, v2
	v_xor_b32_e32 v86, 1, v84
	v_xor_b32_e32 v87, 2, v84
	v_xor_b32_e32 v88, 4, v84
	v_xor_b32_e32 v89, 8, v84
	v_xor_b32_e32 v90, 16, v84
	v_xor_b32_e32 v91, 32, v84
	s_mov_b64 s[6:7], 0x2000
	s_mov_b64 s[8:9], 0x800000
	s_mov_b64 s[10:11], 0x400000
	s_branch .LBB0_2205
